# split-K partial store/reduce of P7/P9/P10 also moved to 16B stores + 16-deep pipelined loads (all six GEMM phases now)
# speedup vs baseline: 1.0233x; 1.0105x over previous
; __device__ __forceinline__ int fresh_tid() { int t = threadIdx.x; asm volatile("" : "+v"(t)); return t; }
; __device__ __forceinline__ bool splitk_fixup(f32x4 (&acc)[2][2][4][2], const Unit& u, const SplitK& sk, int wid, int lane_) {
;     (void)lane_; const int lane = fresh_tid() & 63;
;     typedef unsigned long long u64;
;     u64* mine = (u64*)(sk.part + ((size_t)(u.pn * u.nsplit + u.slice) * 8 + wid) * 8192) + lane;
; #pragma unroll
;     for (int q = 0; q < 32; ++q) { const f32x4 v = acc[q >> 4][(q >> 3) & 1][(q >> 1) & 3][q & 1];
;         __hip_atomic_store(mine + (2 * q) * 64, ((u64)__float_as_uint(v[1]) << 32) | __float_as_uint(v[0]), __ATOMIC_RELAXED, __HIP_MEMORY_SCOPE_AGENT);
;         __hip_atomic_store(mine + (2 * q + 1) * 64, ((u64)__float_as_uint(v[3]) << 32) | __float_as_uint(v[2]), __ATOMIC_RELAXED, __HIP_MEMORY_SCOPE_AGENT); }
;     asm volatile("s_waitcnt vmcnt(0)" ::: "memory");
;     unsigned old = 0; if (lane == 0) old = __hip_atomic_fetch_add(sk.cnt + u.pn * 8 + wid, 1u, __ATOMIC_RELAXED, __HIP_MEMORY_SCOPE_AGENT);
;     old = (unsigned)__builtin_amdgcn_readfirstlane((int)old);
;     if ((old % (unsigned)u.nsplit) != (unsigned)(u.nsplit - 1)) return false;
.LBB0_1069:
	s_mul_i32 s20, s36, s88
	s_add_i32 s40, s20, s42
	s_ashr_i32 s41, s40, 31
	v_mov_b32_e32 v132, v210
	s_lshl_b64 s[40:41], s[40:41], 18
	s_add_u32 s40, s8, s40
	v_and_b32_e32 v142, 63, v132
	s_addc_u32 s41, s9, s41
	v_lshlrev_b32_e32 v132, 4, v142
	v_add_u32_e32 v132, 0x1000, v132
	v_add_u32_e32 v140, 0x2000, v132
	v_add_u32_e32 v141, 0x4000, v132
	v_add_u32_e32 v143, 0x6000, v132
	global_store_dwordx4 v132, v[124:127], s[40:41] offset:-4096 sc1
	global_store_dwordx4 v132, v[120:123], s[40:41] offset:-3072 sc1
	global_store_dwordx4 v132, v[116:119], s[40:41] offset:-2048 sc1
	global_store_dwordx4 v132, v[108:111], s[40:41] offset:-1024 sc1
	global_store_dwordx4 v132, v[96:99], s[40:41] sc1
	global_store_dwordx4 v132, v[92:95], s[40:41] offset:1024 sc1
	global_store_dwordx4 v132, v[80:83], s[40:41] offset:2048 sc1
	global_store_dwordx4 v132, v[76:79], s[40:41] offset:3072 sc1
	global_store_dwordx4 v140, v[112:115], s[40:41] offset:-4096 sc1
	global_store_dwordx4 v140, v[104:107], s[40:41] offset:-3072 sc1
	global_store_dwordx4 v140, v[100:103], s[40:41] offset:-2048 sc1
	global_store_dwordx4 v140, v[88:91], s[40:41] offset:-1024 sc1
	global_store_dwordx4 v140, v[84:87], s[40:41] sc1
	global_store_dwordx4 v140, v[72:75], s[40:41] offset:1024 sc1
	global_store_dwordx4 v140, v[68:71], s[40:41] offset:2048 sc1
	global_store_dwordx4 v140, v[64:67], s[40:41] offset:3072 sc1
	global_store_dwordx4 v141, v[60:63], s[40:41] offset:-4096 sc1
	global_store_dwordx4 v141, v[56:59], s[40:41] offset:-3072 sc1
	global_store_dwordx4 v141, v[48:51], s[40:41] offset:-2048 sc1
	global_store_dwordx4 v141, v[44:47], s[40:41] offset:-1024 sc1
	global_store_dwordx4 v141, v[32:35], s[40:41] sc1
	global_store_dwordx4 v141, v[28:31], s[40:41] offset:1024 sc1
	global_store_dwordx4 v141, v[16:19], s[40:41] offset:2048 sc1
	global_store_dwordx4 v141, v[12:15], s[40:41] offset:3072 sc1
	global_store_dwordx4 v143, v[52:55], s[40:41] offset:-4096 sc1
	global_store_dwordx4 v143, v[40:43], s[40:41] offset:-3072 sc1
	global_store_dwordx4 v143, v[36:39], s[40:41] offset:-2048 sc1
	global_store_dwordx4 v143, v[24:27], s[40:41] offset:-1024 sc1
	global_store_dwordx4 v143, v[20:23], s[40:41] sc1
	global_store_dwordx4 v143, v[8:11], s[40:41] offset:1024 sc1
	global_store_dwordx4 v143, v[4:7], s[40:41] offset:2048 sc1
	global_store_dwordx4 v143, v[0:3], s[40:41] offset:3072 sc1
	s_nop 1
	s_waitcnt vmcnt(0)
	v_mov_b32_e32 v0, 0
	v_cmp_eq_u32_e32 vcc, 0, v142
	s_and_saveexec_b64 s[40:41], vcc
	s_cbranch_execz .LBB0_1073
	s_mov_b64 s[44:45], exec
	v_mbcnt_lo_u32_b32 v0, s44, 0
	v_mbcnt_hi_u32_b32 v0, s45, v0
	v_cmp_eq_u32_e32 vcc, 0, v0
	s_and_saveexec_b64 s[42:43], vcc
	s_cbranch_execz .LBB0_1072
	s_lshl_b32 s90, s36, 3
	s_ashr_i32 s91, s90, 31
	s_lshl_b64 s[90:91], s[90:91], 2
	s_add_u32 s90, s64, s90
	s_addc_u32 s91, s65, s91
	s_bcnt1_i32_b64 s11, s[44:45]
	v_mov_b32_e32 v1, s11
	global_atomic_add v1, v133, v1, s[90:91] sc0

; __device__ __forceinline__ bool splitk_fixup(f32x4 (&acc)[2][2][4][2], const Unit& u, const SplitK& sk, int wid, int lane_) {
;     ...
;     unsigned old = 0; if (lane == 0) old = __hip_atomic_fetch_add(sk.cnt + u.pn * 8 + wid, 1u, __ATOMIC_RELAXED, __HIP_MEMORY_SCOPE_AGENT);
;     old = (unsigned)__builtin_amdgcn_readfirstlane((int)old);
;     if ((old % (unsigned)u.nsplit) != (unsigned)(u.nsplit - 1)) return false;
; #pragma unroll
;     for (int q = 0; q < 32; ++q) acc[q >> 4][(q >> 3) & 1][(q >> 1) & 3][q & 1] = (f32x4){0.f, 0.f, 0.f, 0.f};
;     for (int sl = 0; sl < u.nsplit; ++sl) { u64* p = (u64*)(sk.part + ((size_t)(u.pn * u.nsplit + sl) * 8 + wid) * 8192) + lane;
.LBB0_1073:
	s_or_b64 exec, exec, s[40:41]
	v_cvt_f32_u32_e32 v1, s88
	s_sub_i32 s13, 0, s88
	v_readfirstlane_b32 s11, v0
	v_rcp_iflag_f32_e32 v1, v1
	s_nop 0
	v_mul_f32_e32 v1, 0x4f7ffffe, v1
	v_cvt_u32_f32_e32 v1, v1
	s_nop 0
	v_readfirstlane_b32 s15, v1
	s_mul_i32 s13, s13, s15
	s_mul_hi_u32 s13, s15, s13
	s_add_i32 s15, s15, s13
	s_mul_hi_u32 s13, s11, s15
	s_mul_i32 s13, s13, s88
	s_sub_i32 s11, s11, s13
	s_sub_i32 s13, s11, s88
	s_cmp_ge_u32 s11, s88
	s_cselect_b32 s11, s13, s11
	s_sub_i32 s13, s11, s88
	s_cmp_ge_u32 s11, s88
	s_cselect_b32 s11, s13, s11
	s_add_i32 s13, s88, -1
	s_cmp_lg_u32 s11, s13
	s_cbranch_scc1 .LBB0_1077
	v_mov_b32_e32 v0, 0
	v_mov_b32_e32 v1, 0
	v_mov_b32_e32 v2, 0
	v_mov_b32_e32 v3, 0
	v_mov_b32_e32 v4, 0
	v_mov_b32_e32 v5, 0
	v_mov_b32_e32 v6, 0
	v_mov_b32_e32 v7, 0
	v_mov_b32_e32 v8, 0
	v_mov_b32_e32 v9, 0
	v_mov_b32_e32 v10, 0
	v_mov_b32_e32 v11, 0
	v_mov_b32_e32 v20, 0
	v_mov_b32_e32 v21, 0
	v_mov_b32_e32 v22, 0
	v_mov_b32_e32 v23, 0
	v_mov_b32_e32 v24, 0
	v_mov_b32_e32 v25, 0
	v_mov_b32_e32 v26, 0
	v_mov_b32_e32 v27, 0
	v_mov_b32_e32 v36, 0
	v_mov_b32_e32 v37, 0
	v_mov_b32_e32 v38, 0
	v_mov_b32_e32 v39, 0
	v_mov_b32_e32 v40, 0
	v_mov_b32_e32 v41, 0
	v_mov_b32_e32 v42, 0
	v_mov_b32_e32 v43, 0
	v_mov_b32_e32 v52, 0
	v_mov_b32_e32 v53, 0
	v_mov_b32_e32 v54, 0
	v_mov_b32_e32 v55, 0
	v_mov_b32_e32 v12, 0
	v_mov_b32_e32 v13, 0
	v_mov_b32_e32 v14, 0
	v_mov_b32_e32 v15, 0
	v_mov_b32_e32 v16, 0
	v_mov_b32_e32 v17, 0
	v_mov_b32_e32 v18, 0
	v_mov_b32_e32 v19, 0
	v_mov_b32_e32 v28, 0
	v_mov_b32_e32 v29, 0
	v_mov_b32_e32 v30, 0
	v_mov_b32_e32 v31, 0
	v_mov_b32_e32 v32, 0
	v_mov_b32_e32 v33, 0
	v_mov_b32_e32 v34, 0
	v_mov_b32_e32 v35, 0
	v_mov_b32_e32 v44, 0
	v_mov_b32_e32 v45, 0
	v_mov_b32_e32 v46, 0
	v_mov_b32_e32 v47, 0
	v_mov_b32_e32 v48, 0
	v_mov_b32_e32 v49, 0
	v_mov_b32_e32 v50, 0
	v_mov_b32_e32 v51, 0
	v_mov_b32_e32 v56, 0
	v_mov_b32_e32 v57, 0
	v_mov_b32_e32 v58, 0
	v_mov_b32_e32 v59, 0
	v_mov_b32_e32 v60, 0
	v_mov_b32_e32 v61, 0
	v_mov_b32_e32 v62, 0
	v_mov_b32_e32 v63, 0
	v_mov_b32_e32 v64, 0
	v_mov_b32_e32 v65, 0
	v_mov_b32_e32 v66, 0
	v_mov_b32_e32 v67, 0
	v_mov_b32_e32 v68, 0
	v_mov_b32_e32 v69, 0
	v_mov_b32_e32 v70, 0
	v_mov_b32_e32 v71, 0
	v_mov_b32_e32 v72, 0
	v_mov_b32_e32 v73, 0
	v_mov_b32_e32 v74, 0
	v_mov_b32_e32 v75, 0
	v_mov_b32_e32 v84, 0
	v_mov_b32_e32 v85, 0
	v_mov_b32_e32 v86, 0
	v_mov_b32_e32 v87, 0
	v_mov_b32_e32 v88, 0
	v_mov_b32_e32 v89, 0
	v_mov_b32_e32 v90, 0
	v_mov_b32_e32 v91, 0
	v_mov_b32_e32 v100, 0
	v_mov_b32_e32 v101, 0
	v_mov_b32_e32 v102, 0
	v_mov_b32_e32 v103, 0
	v_mov_b32_e32 v104, 0
	v_mov_b32_e32 v105, 0
	v_mov_b32_e32 v106, 0
	v_mov_b32_e32 v107, 0
	v_mov_b32_e32 v112, 0
	v_mov_b32_e32 v113, 0
	v_mov_b32_e32 v114, 0
	v_mov_b32_e32 v115, 0
	v_mov_b32_e32 v76, 0
	v_mov_b32_e32 v77, 0
	v_mov_b32_e32 v78, 0
	v_mov_b32_e32 v79, 0
	v_mov_b32_e32 v80, 0
	v_mov_b32_e32 v81, 0
	v_mov_b32_e32 v82, 0
	v_mov_b32_e32 v83, 0
	v_mov_b32_e32 v92, 0
	v_mov_b32_e32 v93, 0
	v_mov_b32_e32 v94, 0
	v_mov_b32_e32 v95, 0
	v_mov_b32_e32 v96, 0
	v_mov_b32_e32 v97, 0
	v_mov_b32_e32 v98, 0
	v_mov_b32_e32 v99, 0
	v_mov_b32_e32 v108, 0
	v_mov_b32_e32 v109, 0
	v_mov_b32_e32 v110, 0
	v_mov_b32_e32 v111, 0
	v_mov_b32_e32 v116, 0
	v_mov_b32_e32 v117, 0
	v_mov_b32_e32 v118, 0
	v_mov_b32_e32 v119, 0
	v_mov_b32_e32 v120, 0
	v_mov_b32_e32 v121, 0
	v_mov_b32_e32 v122, 0
	v_mov_b32_e32 v123, 0
	v_mov_b32_e32 v124, 0
	v_mov_b32_e32 v125, 0
	v_mov_b32_e32 v126, 0
	v_mov_b32_e32 v127, 0
.LBB0_1075:
	v_and_b32_e32 v132, 63, v210
	v_lshlrev_b32_e32 v132, 4, v132
	v_add_u32_e32 v132, 0x1000, v132
	v_add_u32_e32 v140, 0x2000, v132
	v_add_u32_e32 v141, 0x4000, v132
	v_add_u32_e32 v143, 0x6000, v132
	s_ashr_i32 s21, s20, 31
	s_lshl_b64 s[38:39], s[20:21], 18
	s_add_u32 s38, s8, s38
	s_addc_u32 s39, s9, s39
	global_load_dwordx4 v[148:151], v132, s[38:39] offset:-4096 sc1
	global_load_dwordx4 v[152:155], v132, s[38:39] offset:-3072 sc1
	global_load_dwordx4 v[156:159], v132, s[38:39] offset:-2048 sc1
	global_load_dwordx4 v[160:163], v132, s[38:39] offset:-1024 sc1
	global_load_dwordx4 v[164:167], v132, s[38:39] sc1
	global_load_dwordx4 v[168:171], v132, s[38:39] offset:1024 sc1
	global_load_dwordx4 v[172:175], v132, s[38:39] offset:2048 sc1
	global_load_dwordx4 v[176:179], v132, s[38:39] offset:3072 sc1
	global_load_dwordx4 v[180:183], v140, s[38:39] offset:-4096 sc1
	global_load_dwordx4 v[184:187], v140, s[38:39] offset:-3072 sc1
	global_load_dwordx4 v[188:191], v140, s[38:39] offset:-2048 sc1
	global_load_dwordx4 v[192:195], v140, s[38:39] offset:-1024 sc1
	global_load_dwordx4 v[196:199], v140, s[38:39] sc1
	global_load_dwordx4 v[200:203], v140, s[38:39] offset:1024 sc1
	global_load_dwordx4 v[204:207], v140, s[38:39] offset:2048 sc1
	global_load_dwordx4 v[212:215], v140, s[38:39] offset:3072 sc1
; __device__ __forceinline__ bool splitk_fixup(f32x4 (&acc)[2][2][4][2], const Unit& u, const SplitK& sk, int wid, int lane_) {
;     ...
;     for (int sl = 0; sl < u.nsplit; ++sl) { u64* p = (u64*)(sk.part + ((size_t)(u.pn * u.nsplit + sl) * 8 + wid) * 8192) + lane;
; #pragma unroll
;         for (int q = 0; q < 32; ++q) { const u64 a = __hip_atomic_load(p + (2 * q) * 64, __ATOMIC_RELAXED, __HIP_MEMORY_SCOPE_AGENT), b = __hip_atomic_load(p + (2 * q + 1) * 64, __ATOMIC_RELAXED, __HIP_MEMORY_SCOPE_AGENT);
;             f32x4& d = acc[q >> 4][(q >> 3) & 1][(q >> 1) & 3][q & 1];
;             d[0] += __uint_as_float((unsigned)a); d[1] += __uint_as_float((unsigned)(a >> 32)); d[2] += __uint_as_float((unsigned)b); d[3] += __uint_as_float((unsigned)(b >> 32)); } }
.Lskr_p7_loop:
	s_add_i32 s88, s88, -1
	s_waitcnt vmcnt(15)
	v_add_f32_e32 v124, v124, v148
	v_add_f32_e32 v125, v125, v149
	v_add_f32_e32 v126, v126, v150
	v_add_f32_e32 v127, v127, v151
	global_load_dwordx4 v[148:151], v141, s[38:39] offset:-4096 sc1
	s_waitcnt vmcnt(15)
	v_add_f32_e32 v120, v120, v152
	v_add_f32_e32 v121, v121, v153
	v_add_f32_e32 v122, v122, v154
	v_add_f32_e32 v123, v123, v155
	global_load_dwordx4 v[152:155], v141, s[38:39] offset:-3072 sc1
	s_waitcnt vmcnt(15)
	v_add_f32_e32 v116, v116, v156
	v_add_f32_e32 v117, v117, v157
	v_add_f32_e32 v118, v118, v158
	v_add_f32_e32 v119, v119, v159
	global_load_dwordx4 v[156:159], v141, s[38:39] offset:-2048 sc1
	s_waitcnt vmcnt(15)
	v_add_f32_e32 v108, v108, v160
	v_add_f32_e32 v109, v109, v161
	v_add_f32_e32 v110, v110, v162
	v_add_f32_e32 v111, v111, v163
	global_load_dwordx4 v[160:163], v141, s[38:39] offset:-1024 sc1
	s_waitcnt vmcnt(15)
	v_add_f32_e32 v96, v96, v164
	v_add_f32_e32 v97, v97, v165
	v_add_f32_e32 v98, v98, v166
	v_add_f32_e32 v99, v99, v167
	global_load_dwordx4 v[164:167], v141, s[38:39] sc1
	s_waitcnt vmcnt(15)
	v_add_f32_e32 v92, v92, v168
	v_add_f32_e32 v93, v93, v169
	v_add_f32_e32 v94, v94, v170
	v_add_f32_e32 v95, v95, v171
	global_load_dwordx4 v[168:171], v141, s[38:39] offset:1024 sc1
	s_waitcnt vmcnt(15)
	v_add_f32_e32 v80, v80, v172
	v_add_f32_e32 v81, v81, v173
	v_add_f32_e32 v82, v82, v174
	v_add_f32_e32 v83, v83, v175
	global_load_dwordx4 v[172:175], v141, s[38:39] offset:2048 sc1
	s_waitcnt vmcnt(15)
	v_add_f32_e32 v76, v76, v176
	v_add_f32_e32 v77, v77, v177
	v_add_f32_e32 v78, v78, v178
	v_add_f32_e32 v79, v79, v179
	global_load_dwordx4 v[176:179], v141, s[38:39] offset:3072 sc1
	s_waitcnt vmcnt(15)
	v_add_f32_e32 v112, v112, v180
	v_add_f32_e32 v113, v113, v181
	v_add_f32_e32 v114, v114, v182
	v_add_f32_e32 v115, v115, v183
	global_load_dwordx4 v[180:183], v143, s[38:39] offset:-4096 sc1
	s_waitcnt vmcnt(15)
	v_add_f32_e32 v104, v104, v184
	v_add_f32_e32 v105, v105, v185
	v_add_f32_e32 v106, v106, v186
	v_add_f32_e32 v107, v107, v187
	global_load_dwordx4 v[184:187], v143, s[38:39] offset:-3072 sc1
	s_waitcnt vmcnt(15)
	v_add_f32_e32 v100, v100, v188
	v_add_f32_e32 v101, v101, v189
	v_add_f32_e32 v102, v102, v190
	v_add_f32_e32 v103, v103, v191
	global_load_dwordx4 v[188:191], v143, s[38:39] offset:-2048 sc1
	s_waitcnt vmcnt(15)
	v_add_f32_e32 v88, v88, v192
	v_add_f32_e32 v89, v89, v193
	v_add_f32_e32 v90, v90, v194
	v_add_f32_e32 v91, v91, v195
	global_load_dwordx4 v[192:195], v143, s[38:39] offset:-1024 sc1
	s_waitcnt vmcnt(15)
	v_add_f32_e32 v84, v84, v196
	v_add_f32_e32 v85, v85, v197
	v_add_f32_e32 v86, v86, v198
	v_add_f32_e32 v87, v87, v199
	global_load_dwordx4 v[196:199], v143, s[38:39] sc1
	s_waitcnt vmcnt(15)
	v_add_f32_e32 v72, v72, v200
	v_add_f32_e32 v73, v73, v201
	v_add_f32_e32 v74, v74, v202
	v_add_f32_e32 v75, v75, v203
	global_load_dwordx4 v[200:203], v143, s[38:39] offset:1024 sc1
	s_waitcnt vmcnt(15)
	v_add_f32_e32 v68, v68, v204
	v_add_f32_e32 v69, v69, v205
	v_add_f32_e32 v70, v70, v206
	v_add_f32_e32 v71, v71, v207
	global_load_dwordx4 v[204:207], v143, s[38:39] offset:2048 sc1
	s_waitcnt vmcnt(15)
	v_add_f32_e32 v64, v64, v212
	v_add_f32_e32 v65, v65, v213
	v_add_f32_e32 v66, v66, v214
	v_add_f32_e32 v67, v67, v215
	global_load_dwordx4 v[212:215], v143, s[38:39] offset:3072 sc1
	s_cmp_lg_u32 s88, 0
	s_addc_u32 s20, s20, 0
	s_ashr_i32 s21, s20, 31
	s_lshl_b64 s[38:39], s[20:21], 18
	s_add_u32 s38, s8, s38
	s_addc_u32 s39, s9, s39
	s_waitcnt vmcnt(15)
	v_add_f32_e32 v60, v60, v148
	v_add_f32_e32 v61, v61, v149
	v_add_f32_e32 v62, v62, v150
	v_add_f32_e32 v63, v63, v151
	global_load_dwordx4 v[148:151], v132, s[38:39] offset:-4096 sc1
	s_waitcnt vmcnt(15)
	v_add_f32_e32 v56, v56, v152
	v_add_f32_e32 v57, v57, v153
	v_add_f32_e32 v58, v58, v154
	v_add_f32_e32 v59, v59, v155
	global_load_dwordx4 v[152:155], v132, s[38:39] offset:-3072 sc1
	s_waitcnt vmcnt(15)
	v_add_f32_e32 v48, v48, v156
	v_add_f32_e32 v49, v49, v157
	v_add_f32_e32 v50, v50, v158
	v_add_f32_e32 v51, v51, v159
	global_load_dwordx4 v[156:159], v132, s[38:39] offset:-2048 sc1
	s_waitcnt vmcnt(15)
	v_add_f32_e32 v44, v44, v160
	v_add_f32_e32 v45, v45, v161
	v_add_f32_e32 v46, v46, v162
	v_add_f32_e32 v47, v47, v163
	global_load_dwordx4 v[160:163], v132, s[38:39] offset:-1024 sc1
	s_waitcnt vmcnt(15)
	v_add_f32_e32 v32, v32, v164
	v_add_f32_e32 v33, v33, v165
	v_add_f32_e32 v34, v34, v166
	v_add_f32_e32 v35, v35, v167
	global_load_dwordx4 v[164:167], v132, s[38:39] sc1
	s_waitcnt vmcnt(15)
	v_add_f32_e32 v28, v28, v168
	v_add_f32_e32 v29, v29, v169
	v_add_f32_e32 v30, v30, v170
	v_add_f32_e32 v31, v31, v171
	global_load_dwordx4 v[168:171], v132, s[38:39] offset:1024 sc1
	s_waitcnt vmcnt(15)
	v_add_f32_e32 v16, v16, v172
	v_add_f32_e32 v17, v17, v173
	v_add_f32_e32 v18, v18, v174
	v_add_f32_e32 v19, v19, v175
	global_load_dwordx4 v[172:175], v132, s[38:39] offset:2048 sc1
	s_waitcnt vmcnt(15)
	v_add_f32_e32 v12, v12, v176
	v_add_f32_e32 v13, v13, v177
	v_add_f32_e32 v14, v14, v178
	v_add_f32_e32 v15, v15, v179
	global_load_dwordx4 v[176:179], v132, s[38:39] offset:3072 sc1
	s_waitcnt vmcnt(15)
	v_add_f32_e32 v52, v52, v180
	v_add_f32_e32 v53, v53, v181
	v_add_f32_e32 v54, v54, v182
	v_add_f32_e32 v55, v55, v183
	global_load_dwordx4 v[180:183], v140, s[38:39] offset:-4096 sc1
	s_waitcnt vmcnt(15)
	v_add_f32_e32 v40, v40, v184
	v_add_f32_e32 v41, v41, v185
	v_add_f32_e32 v42, v42, v186
	v_add_f32_e32 v43, v43, v187
	global_load_dwordx4 v[184:187], v140, s[38:39] offset:-3072 sc1
	s_waitcnt vmcnt(15)
	v_add_f32_e32 v36, v36, v188
	v_add_f32_e32 v37, v37, v189
	v_add_f32_e32 v38, v38, v190
	v_add_f32_e32 v39, v39, v191
	global_load_dwordx4 v[188:191], v140, s[38:39] offset:-2048 sc1
	s_waitcnt vmcnt(15)
	v_add_f32_e32 v24, v24, v192
	v_add_f32_e32 v25, v25, v193
	v_add_f32_e32 v26, v26, v194
	v_add_f32_e32 v27, v27, v195
	global_load_dwordx4 v[192:195], v140, s[38:39] offset:-1024 sc1
	s_waitcnt vmcnt(15)
	v_add_f32_e32 v20, v20, v196
	v_add_f32_e32 v21, v21, v197
	v_add_f32_e32 v22, v22, v198
	v_add_f32_e32 v23, v23, v199
	global_load_dwordx4 v[196:199], v140, s[38:39] sc1
	s_waitcnt vmcnt(15)
	v_add_f32_e32 v8, v8, v200
	v_add_f32_e32 v9, v9, v201
	v_add_f32_e32 v10, v10, v202
	v_add_f32_e32 v11, v11, v203
	global_load_dwordx4 v[200:203], v140, s[38:39] offset:1024 sc1
	s_waitcnt vmcnt(15)
	v_add_f32_e32 v4, v4, v204
	v_add_f32_e32 v5, v5, v205
	v_add_f32_e32 v6, v6, v206
	v_add_f32_e32 v7, v7, v207
	global_load_dwordx4 v[204:207], v140, s[38:39] offset:2048 sc1
	s_waitcnt vmcnt(15)
	v_add_f32_e32 v0, v0, v212
	v_add_f32_e32 v1, v1, v213
	v_add_f32_e32 v2, v2, v214
	v_add_f32_e32 v3, v3, v215
	global_load_dwordx4 v[212:215], v140, s[38:39] offset:3072 sc1
	s_cmp_lg_u32 s88, 0
	s_cbranch_scc1 .Lskr_p7_loop
	s_waitcnt vmcnt(0)
	s_add_i32 s20, s20, 1
	s_mov_b64 s[38:39], -1

; __device__ __forceinline__ int fresh_tid() { int t = threadIdx.x; asm volatile("" : "+v"(t)); return t; }
; __device__ __forceinline__ bool splitk_fixup(f32x4 (&acc)[2][2][4][2], const Unit& u, const SplitK& sk, int wid, int lane_) {
;     (void)lane_; const int lane = fresh_tid() & 63;
;     typedef unsigned long long u64;
;     u64* mine = (u64*)(sk.part + ((size_t)(u.pn * u.nsplit + u.slice) * 8 + wid) * 8192) + lane;
; #pragma unroll
;     for (int q = 0; q < 32; ++q) { const f32x4 v = acc[q >> 4][(q >> 3) & 1][(q >> 1) & 3][q & 1];
;         __hip_atomic_store(mine + (2 * q) * 64, ((u64)__float_as_uint(v[1]) << 32) | __float_as_uint(v[0]), __ATOMIC_RELAXED, __HIP_MEMORY_SCOPE_AGENT);
;         __hip_atomic_store(mine + (2 * q + 1) * 64, ((u64)__float_as_uint(v[3]) << 32) | __float_as_uint(v[2]), __ATOMIC_RELAXED, __HIP_MEMORY_SCOPE_AGENT); }
;     asm volatile("s_waitcnt vmcnt(0)" ::: "memory");
;     unsigned old = 0; if (lane == 0) old = __hip_atomic_fetch_add(sk.cnt + u.pn * 8 + wid, 1u, __ATOMIC_RELAXED, __HIP_MEMORY_SCOPE_AGENT);
;     old = (unsigned)__builtin_amdgcn_readfirstlane((int)old);
;     if ((old % (unsigned)u.nsplit) != (unsigned)(u.nsplit - 1)) return false;
.LBB0_1229:
	s_mul_i32 s20, s73, s36
	s_add_i32 s40, s20, s42
	s_ashr_i32 s41, s40, 31
	v_mov_b32_e32 v136, v210
	s_lshl_b64 s[40:41], s[40:41], 18
	s_add_u32 s40, s12, s40
	v_and_b32_e32 v147, 63, v136
	s_addc_u32 s41, s13, s41
	v_lshlrev_b32_e32 v136, 4, v147
	v_add_u32_e32 v136, 0x1000, v136
	v_add_u32_e32 v144, 0x2000, v136
	v_add_u32_e32 v145, 0x4000, v136
	v_add_u32_e32 v224, 0x6000, v136
	global_store_dwordx4 v136, v[124:127], s[40:41] offset:-4096 sc1
	global_store_dwordx4 v136, v[116:119], s[40:41] offset:-3072 sc1
	global_store_dwordx4 v136, v[108:111], s[40:41] offset:-2048 sc1
	global_store_dwordx4 v136, v[100:103], s[40:41] offset:-1024 sc1
	global_store_dwordx4 v136, v[92:95], s[40:41] sc1
	global_store_dwordx4 v136, v[84:87], s[40:41] offset:1024 sc1
	global_store_dwordx4 v136, v[76:79], s[40:41] offset:2048 sc1
	global_store_dwordx4 v136, v[68:71], s[40:41] offset:3072 sc1
	global_store_dwordx4 v144, v[120:123], s[40:41] offset:-4096 sc1
	global_store_dwordx4 v144, v[112:115], s[40:41] offset:-3072 sc1
	global_store_dwordx4 v144, v[104:107], s[40:41] offset:-2048 sc1
	global_store_dwordx4 v144, v[96:99], s[40:41] offset:-1024 sc1
	global_store_dwordx4 v144, v[88:91], s[40:41] sc1
	global_store_dwordx4 v144, v[80:83], s[40:41] offset:1024 sc1
	global_store_dwordx4 v144, v[72:75], s[40:41] offset:2048 sc1
	global_store_dwordx4 v144, v[64:67], s[40:41] offset:3072 sc1
	global_store_dwordx4 v145, v[60:63], s[40:41] offset:-4096 sc1
	global_store_dwordx4 v145, v[52:55], s[40:41] offset:-3072 sc1
	global_store_dwordx4 v145, v[44:47], s[40:41] offset:-2048 sc1
	global_store_dwordx4 v145, v[36:39], s[40:41] offset:-1024 sc1
	global_store_dwordx4 v145, v[28:31], s[40:41] sc1
	global_store_dwordx4 v145, v[20:23], s[40:41] offset:1024 sc1
	global_store_dwordx4 v145, v[12:15], s[40:41] offset:2048 sc1
	global_store_dwordx4 v145, v[4:7], s[40:41] offset:3072 sc1
	global_store_dwordx4 v224, v[56:59], s[40:41] offset:-4096 sc1
	global_store_dwordx4 v224, v[48:51], s[40:41] offset:-3072 sc1
	global_store_dwordx4 v224, v[40:43], s[40:41] offset:-2048 sc1
	global_store_dwordx4 v224, v[32:35], s[40:41] offset:-1024 sc1
	global_store_dwordx4 v224, v[24:27], s[40:41] sc1
	global_store_dwordx4 v224, v[16:19], s[40:41] offset:1024 sc1
	global_store_dwordx4 v224, v[8:11], s[40:41] offset:2048 sc1
	global_store_dwordx4 v224, v[0:3], s[40:41] offset:3072 sc1
	s_nop 1
	s_waitcnt vmcnt(0)
	v_mov_b32_e32 v0, 0
	v_cmp_eq_u32_e32 vcc, 0, v147
	s_and_saveexec_b64 s[40:41], vcc
	s_cbranch_execz .LBB0_1233
	s_mov_b64 s[44:45], exec
	v_mbcnt_lo_u32_b32 v0, s44, 0
	v_mbcnt_hi_u32_b32 v0, s45, v0
	v_cmp_eq_u32_e32 vcc, 0, v0
	s_and_saveexec_b64 s[42:43], vcc
	s_cbranch_execz .LBB0_1232
	s_lshl_b32 s76, s36, 3
	s_ashr_i32 s77, s76, 31
	s_lshl_b64 s[76:77], s[76:77], 2
	s_add_u32 s76, s60, s76
	s_addc_u32 s77, s61, s77
	s_bcnt1_i32_b64 s3, s[44:45]
	v_mov_b32_e32 v1, s3
	global_atomic_add v1, v137, v1, s[76:77] sc0

; __device__ __forceinline__ bool splitk_fixup(f32x4 (&acc)[2][2][4][2], const Unit& u, const SplitK& sk, int wid, int lane_) {
;     ...
;     unsigned old = 0; if (lane == 0) old = __hip_atomic_fetch_add(sk.cnt + u.pn * 8 + wid, 1u, __ATOMIC_RELAXED, __HIP_MEMORY_SCOPE_AGENT);
;     old = (unsigned)__builtin_amdgcn_readfirstlane((int)old);
;     if ((old % (unsigned)u.nsplit) != (unsigned)(u.nsplit - 1)) return false;
; #pragma unroll
;     for (int q = 0; q < 32; ++q) acc[q >> 4][(q >> 3) & 1][(q >> 1) & 3][q & 1] = (f32x4){0.f, 0.f, 0.f, 0.f};
;     for (int sl = 0; sl < u.nsplit; ++sl) { u64* p = (u64*)(sk.part + ((size_t)(u.pn * u.nsplit + sl) * 8 + wid) * 8192) + lane;
.LBB0_1233:
	s_or_b64 exec, exec, s[40:41]
	v_cvt_f32_u32_e32 v1, s73
	s_sub_i32 s15, 0, s73
	v_readfirstlane_b32 s3, v0
	v_rcp_iflag_f32_e32 v1, v1
	s_nop 0
	v_mul_f32_e32 v1, 0x4f7ffffe, v1
	v_cvt_u32_f32_e32 v1, v1
	s_nop 0
	v_readfirstlane_b32 s17, v1
	s_mul_i32 s15, s15, s17
	s_mul_hi_u32 s15, s17, s15
	s_add_i32 s17, s17, s15
	s_mul_hi_u32 s15, s3, s17
	s_mul_i32 s15, s15, s73
	s_sub_i32 s3, s3, s15
	s_sub_i32 s15, s3, s73
	s_cmp_ge_u32 s3, s73
	s_cselect_b32 s3, s15, s3
	s_sub_i32 s15, s3, s73
	s_cmp_ge_u32 s3, s73
	s_cselect_b32 s3, s15, s3
	s_add_i32 s15, s73, -1
	s_cmp_lg_u32 s3, s15
	s_cbranch_scc1 .LBB0_1237
	v_mov_b32_e32 v0, 0
	v_mov_b32_e32 v1, 0
	v_mov_b32_e32 v2, 0
	v_mov_b32_e32 v3, 0
	v_mov_b32_e32 v8, 0
	v_mov_b32_e32 v9, 0
	v_mov_b32_e32 v10, 0
	v_mov_b32_e32 v11, 0
	v_mov_b32_e32 v16, 0
	v_mov_b32_e32 v17, 0
	v_mov_b32_e32 v18, 0
	v_mov_b32_e32 v19, 0
	v_mov_b32_e32 v24, 0
	v_mov_b32_e32 v25, 0
	v_mov_b32_e32 v26, 0
	v_mov_b32_e32 v27, 0
	v_mov_b32_e32 v32, 0
	v_mov_b32_e32 v33, 0
	v_mov_b32_e32 v34, 0
	v_mov_b32_e32 v35, 0
	v_mov_b32_e32 v40, 0
	v_mov_b32_e32 v41, 0
	v_mov_b32_e32 v42, 0
	v_mov_b32_e32 v43, 0
	v_mov_b32_e32 v48, 0
	v_mov_b32_e32 v49, 0
	v_mov_b32_e32 v50, 0
	v_mov_b32_e32 v51, 0
	v_mov_b32_e32 v56, 0
	v_mov_b32_e32 v57, 0
	v_mov_b32_e32 v58, 0
	v_mov_b32_e32 v59, 0
	v_mov_b32_e32 v4, 0
	v_mov_b32_e32 v5, 0
	v_mov_b32_e32 v6, 0
	v_mov_b32_e32 v7, 0
	v_mov_b32_e32 v12, 0
	v_mov_b32_e32 v13, 0
	v_mov_b32_e32 v14, 0
	v_mov_b32_e32 v15, 0
	v_mov_b32_e32 v20, 0
	v_mov_b32_e32 v21, 0
	v_mov_b32_e32 v22, 0
	v_mov_b32_e32 v23, 0
	v_mov_b32_e32 v28, 0
	v_mov_b32_e32 v29, 0
	v_mov_b32_e32 v30, 0
	v_mov_b32_e32 v31, 0
	v_mov_b32_e32 v36, 0
	v_mov_b32_e32 v37, 0
	v_mov_b32_e32 v38, 0
	v_mov_b32_e32 v39, 0
	v_mov_b32_e32 v44, 0
	v_mov_b32_e32 v45, 0
	v_mov_b32_e32 v46, 0
	v_mov_b32_e32 v47, 0
	v_mov_b32_e32 v52, 0
	v_mov_b32_e32 v53, 0
	v_mov_b32_e32 v54, 0
	v_mov_b32_e32 v55, 0
	v_mov_b32_e32 v60, 0
	v_mov_b32_e32 v61, 0
	v_mov_b32_e32 v62, 0
	v_mov_b32_e32 v63, 0
	v_mov_b32_e32 v64, 0
	v_mov_b32_e32 v65, 0
	v_mov_b32_e32 v66, 0
	v_mov_b32_e32 v67, 0
	v_mov_b32_e32 v72, 0
	v_mov_b32_e32 v73, 0
	v_mov_b32_e32 v74, 0
	v_mov_b32_e32 v75, 0
	v_mov_b32_e32 v80, 0
	v_mov_b32_e32 v81, 0
	v_mov_b32_e32 v82, 0
	v_mov_b32_e32 v83, 0
	v_mov_b32_e32 v88, 0
	v_mov_b32_e32 v89, 0
	v_mov_b32_e32 v90, 0
	v_mov_b32_e32 v91, 0
	v_mov_b32_e32 v96, 0
	v_mov_b32_e32 v97, 0
	v_mov_b32_e32 v98, 0
	v_mov_b32_e32 v99, 0
	v_mov_b32_e32 v104, 0
	v_mov_b32_e32 v105, 0
	v_mov_b32_e32 v106, 0
	v_mov_b32_e32 v107, 0
	v_mov_b32_e32 v112, 0
	v_mov_b32_e32 v113, 0
	v_mov_b32_e32 v114, 0
	v_mov_b32_e32 v115, 0
	v_mov_b32_e32 v120, 0
	v_mov_b32_e32 v121, 0
	v_mov_b32_e32 v122, 0
	v_mov_b32_e32 v123, 0
	v_mov_b32_e32 v68, 0
	v_mov_b32_e32 v69, 0
	v_mov_b32_e32 v70, 0
	v_mov_b32_e32 v71, 0
	v_mov_b32_e32 v76, 0
	v_mov_b32_e32 v77, 0
	v_mov_b32_e32 v78, 0
	v_mov_b32_e32 v79, 0
	v_mov_b32_e32 v84, 0
	v_mov_b32_e32 v85, 0
	v_mov_b32_e32 v86, 0
	v_mov_b32_e32 v87, 0
	v_mov_b32_e32 v92, 0
	v_mov_b32_e32 v93, 0
	v_mov_b32_e32 v94, 0
	v_mov_b32_e32 v95, 0
	v_mov_b32_e32 v100, 0
	v_mov_b32_e32 v101, 0
	v_mov_b32_e32 v102, 0
	v_mov_b32_e32 v103, 0
	v_mov_b32_e32 v108, 0
	v_mov_b32_e32 v109, 0
	v_mov_b32_e32 v110, 0
	v_mov_b32_e32 v111, 0
	v_mov_b32_e32 v116, 0
	v_mov_b32_e32 v117, 0
	v_mov_b32_e32 v118, 0
	v_mov_b32_e32 v119, 0
	v_mov_b32_e32 v124, 0
	v_mov_b32_e32 v125, 0
	v_mov_b32_e32 v126, 0
	v_mov_b32_e32 v127, 0
.LBB0_1235:
	v_and_b32_e32 v136, 63, v210
	v_lshlrev_b32_e32 v136, 4, v136
	v_add_u32_e32 v136, 0x1000, v136
	v_add_u32_e32 v144, 0x2000, v136
	v_add_u32_e32 v145, 0x4000, v136
	v_add_u32_e32 v224, 0x6000, v136
	s_ashr_i32 s21, s20, 31
	s_lshl_b64 s[38:39], s[20:21], 18
	s_add_u32 s38, s12, s38
	s_addc_u32 s39, s13, s39
	global_load_dwordx4 v[158:161], v136, s[38:39] offset:-4096 sc1
	global_load_dwordx4 v[162:165], v136, s[38:39] offset:-3072 sc1
	global_load_dwordx4 v[166:169], v136, s[38:39] offset:-2048 sc1
	global_load_dwordx4 v[170:173], v136, s[38:39] offset:-1024 sc1
	global_load_dwordx4 v[174:177], v136, s[38:39] sc1
	global_load_dwordx4 v[178:181], v136, s[38:39] offset:1024 sc1
	global_load_dwordx4 v[182:185], v136, s[38:39] offset:2048 sc1
	global_load_dwordx4 v[186:189], v136, s[38:39] offset:3072 sc1
	global_load_dwordx4 v[190:193], v144, s[38:39] offset:-4096 sc1
	global_load_dwordx4 v[194:197], v144, s[38:39] offset:-3072 sc1
	global_load_dwordx4 v[198:201], v144, s[38:39] offset:-2048 sc1
	global_load_dwordx4 v[202:205], v144, s[38:39] offset:-1024 sc1
	global_load_dwordx4 v[206:209], v144, s[38:39] sc1
	global_load_dwordx4 v[212:215], v144, s[38:39] offset:1024 sc1
	global_load_dwordx4 v[216:219], v144, s[38:39] offset:2048 sc1
	global_load_dwordx4 v[220:223], v144, s[38:39] offset:3072 sc1
; __device__ __forceinline__ bool splitk_fixup(f32x4 (&acc)[2][2][4][2], const Unit& u, const SplitK& sk, int wid, int lane_) {
;     ...
;     for (int sl = 0; sl < u.nsplit; ++sl) { u64* p = (u64*)(sk.part + ((size_t)(u.pn * u.nsplit + sl) * 8 + wid) * 8192) + lane;
; #pragma unroll
;         for (int q = 0; q < 32; ++q) { const u64 a = __hip_atomic_load(p + (2 * q) * 64, __ATOMIC_RELAXED, __HIP_MEMORY_SCOPE_AGENT), b = __hip_atomic_load(p + (2 * q + 1) * 64, __ATOMIC_RELAXED, __HIP_MEMORY_SCOPE_AGENT);
;             f32x4& d = acc[q >> 4][(q >> 3) & 1][(q >> 1) & 3][q & 1];
;             d[0] += __uint_as_float((unsigned)a); d[1] += __uint_as_float((unsigned)(a >> 32)); d[2] += __uint_as_float((unsigned)b); d[3] += __uint_as_float((unsigned)(b >> 32)); } }
.Lskr_p9_loop:
	s_add_i32 s73, s73, -1
	s_waitcnt vmcnt(15)
	v_add_f32_e32 v124, v124, v158
	v_add_f32_e32 v125, v125, v159
	v_add_f32_e32 v126, v126, v160
	v_add_f32_e32 v127, v127, v161
	global_load_dwordx4 v[158:161], v145, s[38:39] offset:-4096 sc1
	s_waitcnt vmcnt(15)
	v_add_f32_e32 v116, v116, v162
	v_add_f32_e32 v117, v117, v163
	v_add_f32_e32 v118, v118, v164
	v_add_f32_e32 v119, v119, v165
	global_load_dwordx4 v[162:165], v145, s[38:39] offset:-3072 sc1
	s_waitcnt vmcnt(15)
	v_add_f32_e32 v108, v108, v166
	v_add_f32_e32 v109, v109, v167
	v_add_f32_e32 v110, v110, v168
	v_add_f32_e32 v111, v111, v169
	global_load_dwordx4 v[166:169], v145, s[38:39] offset:-2048 sc1
	s_waitcnt vmcnt(15)
	v_add_f32_e32 v100, v100, v170
	v_add_f32_e32 v101, v101, v171
	v_add_f32_e32 v102, v102, v172
	v_add_f32_e32 v103, v103, v173
	global_load_dwordx4 v[170:173], v145, s[38:39] offset:-1024 sc1
	s_waitcnt vmcnt(15)
	v_add_f32_e32 v92, v92, v174
	v_add_f32_e32 v93, v93, v175
	v_add_f32_e32 v94, v94, v176
	v_add_f32_e32 v95, v95, v177
	global_load_dwordx4 v[174:177], v145, s[38:39] sc1
	s_waitcnt vmcnt(15)
	v_add_f32_e32 v84, v84, v178
	v_add_f32_e32 v85, v85, v179
	v_add_f32_e32 v86, v86, v180
	v_add_f32_e32 v87, v87, v181
	global_load_dwordx4 v[178:181], v145, s[38:39] offset:1024 sc1
	s_waitcnt vmcnt(15)
	v_add_f32_e32 v76, v76, v182
	v_add_f32_e32 v77, v77, v183
	v_add_f32_e32 v78, v78, v184
	v_add_f32_e32 v79, v79, v185
	global_load_dwordx4 v[182:185], v145, s[38:39] offset:2048 sc1
	s_waitcnt vmcnt(15)
	v_add_f32_e32 v68, v68, v186
	v_add_f32_e32 v69, v69, v187
	v_add_f32_e32 v70, v70, v188
	v_add_f32_e32 v71, v71, v189
	global_load_dwordx4 v[186:189], v145, s[38:39] offset:3072 sc1
	s_waitcnt vmcnt(15)
	v_add_f32_e32 v120, v120, v190
	v_add_f32_e32 v121, v121, v191
	v_add_f32_e32 v122, v122, v192
	v_add_f32_e32 v123, v123, v193
	global_load_dwordx4 v[190:193], v224, s[38:39] offset:-4096 sc1
	s_waitcnt vmcnt(15)
	v_add_f32_e32 v112, v112, v194
	v_add_f32_e32 v113, v113, v195
	v_add_f32_e32 v114, v114, v196
	v_add_f32_e32 v115, v115, v197
	global_load_dwordx4 v[194:197], v224, s[38:39] offset:-3072 sc1
	s_waitcnt vmcnt(15)
	v_add_f32_e32 v104, v104, v198
	v_add_f32_e32 v105, v105, v199
	v_add_f32_e32 v106, v106, v200
	v_add_f32_e32 v107, v107, v201
	global_load_dwordx4 v[198:201], v224, s[38:39] offset:-2048 sc1
	s_waitcnt vmcnt(15)
	v_add_f32_e32 v96, v96, v202
	v_add_f32_e32 v97, v97, v203
	v_add_f32_e32 v98, v98, v204
	v_add_f32_e32 v99, v99, v205
	global_load_dwordx4 v[202:205], v224, s[38:39] offset:-1024 sc1
	s_waitcnt vmcnt(15)
	v_add_f32_e32 v88, v88, v206
	v_add_f32_e32 v89, v89, v207
	v_add_f32_e32 v90, v90, v208
	v_add_f32_e32 v91, v91, v209
	global_load_dwordx4 v[206:209], v224, s[38:39] sc1
	s_waitcnt vmcnt(15)
	v_add_f32_e32 v80, v80, v212
	v_add_f32_e32 v81, v81, v213
	v_add_f32_e32 v82, v82, v214
	v_add_f32_e32 v83, v83, v215
	global_load_dwordx4 v[212:215], v224, s[38:39] offset:1024 sc1
	s_waitcnt vmcnt(15)
	v_add_f32_e32 v72, v72, v216
	v_add_f32_e32 v73, v73, v217
	v_add_f32_e32 v74, v74, v218
	v_add_f32_e32 v75, v75, v219
	global_load_dwordx4 v[216:219], v224, s[38:39] offset:2048 sc1
	s_waitcnt vmcnt(15)
	v_add_f32_e32 v64, v64, v220
	v_add_f32_e32 v65, v65, v221
	v_add_f32_e32 v66, v66, v222
	v_add_f32_e32 v67, v67, v223
	global_load_dwordx4 v[220:223], v224, s[38:39] offset:3072 sc1
	s_cmp_lg_u32 s73, 0
	s_addc_u32 s20, s20, 0
	s_ashr_i32 s21, s20, 31
	s_lshl_b64 s[38:39], s[20:21], 18
	s_add_u32 s38, s12, s38
	s_addc_u32 s39, s13, s39
	s_waitcnt vmcnt(15)
	v_add_f32_e32 v60, v60, v158
	v_add_f32_e32 v61, v61, v159
	v_add_f32_e32 v62, v62, v160
	v_add_f32_e32 v63, v63, v161
	global_load_dwordx4 v[158:161], v136, s[38:39] offset:-4096 sc1
	s_waitcnt vmcnt(15)
	v_add_f32_e32 v52, v52, v162
	v_add_f32_e32 v53, v53, v163
	v_add_f32_e32 v54, v54, v164
	v_add_f32_e32 v55, v55, v165
	global_load_dwordx4 v[162:165], v136, s[38:39] offset:-3072 sc1
	s_waitcnt vmcnt(15)
	v_add_f32_e32 v44, v44, v166
	v_add_f32_e32 v45, v45, v167
	v_add_f32_e32 v46, v46, v168
	v_add_f32_e32 v47, v47, v169
	global_load_dwordx4 v[166:169], v136, s[38:39] offset:-2048 sc1
	s_waitcnt vmcnt(15)
	v_add_f32_e32 v36, v36, v170
	v_add_f32_e32 v37, v37, v171
	v_add_f32_e32 v38, v38, v172
	v_add_f32_e32 v39, v39, v173
	global_load_dwordx4 v[170:173], v136, s[38:39] offset:-1024 sc1
	s_waitcnt vmcnt(15)
	v_add_f32_e32 v28, v28, v174
	v_add_f32_e32 v29, v29, v175
	v_add_f32_e32 v30, v30, v176
	v_add_f32_e32 v31, v31, v177
	global_load_dwordx4 v[174:177], v136, s[38:39] sc1
	s_waitcnt vmcnt(15)
	v_add_f32_e32 v20, v20, v178
	v_add_f32_e32 v21, v21, v179
	v_add_f32_e32 v22, v22, v180
	v_add_f32_e32 v23, v23, v181
	global_load_dwordx4 v[178:181], v136, s[38:39] offset:1024 sc1
	s_waitcnt vmcnt(15)
	v_add_f32_e32 v12, v12, v182
	v_add_f32_e32 v13, v13, v183
	v_add_f32_e32 v14, v14, v184
	v_add_f32_e32 v15, v15, v185
	global_load_dwordx4 v[182:185], v136, s[38:39] offset:2048 sc1
	s_waitcnt vmcnt(15)
	v_add_f32_e32 v4, v4, v186
	v_add_f32_e32 v5, v5, v187
	v_add_f32_e32 v6, v6, v188
	v_add_f32_e32 v7, v7, v189
	global_load_dwordx4 v[186:189], v136, s[38:39] offset:3072 sc1
	s_waitcnt vmcnt(15)
	v_add_f32_e32 v56, v56, v190
	v_add_f32_e32 v57, v57, v191
	v_add_f32_e32 v58, v58, v192
	v_add_f32_e32 v59, v59, v193
	global_load_dwordx4 v[190:193], v144, s[38:39] offset:-4096 sc1
	s_waitcnt vmcnt(15)
	v_add_f32_e32 v48, v48, v194
	v_add_f32_e32 v49, v49, v195
	v_add_f32_e32 v50, v50, v196
	v_add_f32_e32 v51, v51, v197
	global_load_dwordx4 v[194:197], v144, s[38:39] offset:-3072 sc1
	s_waitcnt vmcnt(15)
	v_add_f32_e32 v40, v40, v198
	v_add_f32_e32 v41, v41, v199
	v_add_f32_e32 v42, v42, v200
	v_add_f32_e32 v43, v43, v201
	global_load_dwordx4 v[198:201], v144, s[38:39] offset:-2048 sc1
	s_waitcnt vmcnt(15)
	v_add_f32_e32 v32, v32, v202
	v_add_f32_e32 v33, v33, v203
	v_add_f32_e32 v34, v34, v204
	v_add_f32_e32 v35, v35, v205
	global_load_dwordx4 v[202:205], v144, s[38:39] offset:-1024 sc1
	s_waitcnt vmcnt(15)
	v_add_f32_e32 v24, v24, v206
	v_add_f32_e32 v25, v25, v207
	v_add_f32_e32 v26, v26, v208
	v_add_f32_e32 v27, v27, v209
	global_load_dwordx4 v[206:209], v144, s[38:39] sc1
	s_waitcnt vmcnt(15)
	v_add_f32_e32 v16, v16, v212
	v_add_f32_e32 v17, v17, v213
	v_add_f32_e32 v18, v18, v214
	v_add_f32_e32 v19, v19, v215
	global_load_dwordx4 v[212:215], v144, s[38:39] offset:1024 sc1
	s_waitcnt vmcnt(15)
	v_add_f32_e32 v8, v8, v216
	v_add_f32_e32 v9, v9, v217
	v_add_f32_e32 v10, v10, v218
	v_add_f32_e32 v11, v11, v219
	global_load_dwordx4 v[216:219], v144, s[38:39] offset:2048 sc1
	s_waitcnt vmcnt(15)
	v_add_f32_e32 v0, v0, v220
	v_add_f32_e32 v1, v1, v221
	v_add_f32_e32 v2, v2, v222
	v_add_f32_e32 v3, v3, v223
	global_load_dwordx4 v[220:223], v144, s[38:39] offset:3072 sc1
	s_cmp_lg_u32 s73, 0
	s_cbranch_scc1 .Lskr_p9_loop
	s_waitcnt vmcnt(0)
	s_add_i32 s20, s20, 1
	s_mov_b64 s[38:39], -1

; __device__ __forceinline__ int fresh_tid() { int t = threadIdx.x; asm volatile("" : "+v"(t)); return t; }
; __device__ __forceinline__ bool splitk_fixup(f32x4 (&acc)[2][2][4][2], const Unit& u, const SplitK& sk, int wid, int lane_) {
;     (void)lane_; const int lane = fresh_tid() & 63;
;     typedef unsigned long long u64;
;     u64* mine = (u64*)(sk.part + ((size_t)(u.pn * u.nsplit + u.slice) * 8 + wid) * 8192) + lane;
; #pragma unroll
;     for (int q = 0; q < 32; ++q) { const f32x4 v = acc[q >> 4][(q >> 3) & 1][(q >> 1) & 3][q & 1];
;         __hip_atomic_store(mine + (2 * q) * 64, ((u64)__float_as_uint(v[1]) << 32) | __float_as_uint(v[0]), __ATOMIC_RELAXED, __HIP_MEMORY_SCOPE_AGENT);
;         __hip_atomic_store(mine + (2 * q + 1) * 64, ((u64)__float_as_uint(v[3]) << 32) | __float_as_uint(v[2]), __ATOMIC_RELAXED, __HIP_MEMORY_SCOPE_AGENT); }
;     asm volatile("s_waitcnt vmcnt(0)" ::: "memory");
;     unsigned old = 0; if (lane == 0) old = __hip_atomic_fetch_add(sk.cnt + u.pn * 8 + wid, 1u, __ATOMIC_RELAXED, __HIP_MEMORY_SCOPE_AGENT);
;     old = (unsigned)__builtin_amdgcn_readfirstlane((int)old);
;     if ((old % (unsigned)u.nsplit) != (unsigned)(u.nsplit - 1)) return false;
.LBB0_1335:
	s_mul_i32 s20, s81, s83
	s_add_i32 s34, s20, s36
	s_ashr_i32 s35, s34, 31
	v_mov_b32_e32 v0, v210
	s_lshl_b64 s[34:35], s[34:35], 18
	s_add_u32 s34, s10, s34
	v_and_b32_e32 v6, 63, v0
	s_addc_u32 s35, s11, s35
	v_lshlrev_b32_e32 v164, 4, v6
	v_add_u32_e32 v164, 0x1000, v164
	v_add_u32_e32 v0, 0x2000, v164
	v_add_u32_e32 v1, 0x4000, v164
	v_add_u32_e32 v2, 0x6000, v164
	global_store_dwordx4 v164, v[156:159], s[34:35] offset:-4096 sc1
	global_store_dwordx4 v164, v[152:155], s[34:35] offset:-3072 sc1
	global_store_dwordx4 v164, v[144:147], s[34:35] offset:-2048 sc1
	global_store_dwordx4 v164, v[140:143], s[34:35] offset:-1024 sc1
	global_store_dwordx4 v164, v[128:131], s[34:35] sc1
	global_store_dwordx4 v164, v[124:127], s[34:35] offset:1024 sc1
	global_store_dwordx4 v164, v[112:115], s[34:35] offset:2048 sc1
	global_store_dwordx4 v164, v[108:111], s[34:35] offset:3072 sc1
	global_store_dwordx4 v0, v[148:151], s[34:35] offset:-4096 sc1
	global_store_dwordx4 v0, v[136:139], s[34:35] offset:-3072 sc1
	global_store_dwordx4 v0, v[132:135], s[34:35] offset:-2048 sc1
	global_store_dwordx4 v0, v[120:123], s[34:35] offset:-1024 sc1
	global_store_dwordx4 v0, v[116:119], s[34:35] sc1
	global_store_dwordx4 v0, v[104:107], s[34:35] offset:1024 sc1
	global_store_dwordx4 v0, v[100:103], s[34:35] offset:2048 sc1
	global_store_dwordx4 v0, v[96:99], s[34:35] offset:3072 sc1
	global_store_dwordx4 v1, v[92:95], s[34:35] offset:-4096 sc1
	global_store_dwordx4 v1, v[88:91], s[34:35] offset:-3072 sc1
	global_store_dwordx4 v1, v[80:83], s[34:35] offset:-2048 sc1
	global_store_dwordx4 v1, v[76:79], s[34:35] offset:-1024 sc1
	global_store_dwordx4 v1, v[64:67], s[34:35] sc1
	global_store_dwordx4 v1, v[60:63], s[34:35] offset:1024 sc1
	global_store_dwordx4 v1, v[48:51], s[34:35] offset:2048 sc1
	global_store_dwordx4 v1, v[44:47], s[34:35] offset:3072 sc1
	global_store_dwordx4 v2, v[84:87], s[34:35] offset:-4096 sc1
	global_store_dwordx4 v2, v[72:75], s[34:35] offset:-3072 sc1
	global_store_dwordx4 v2, v[68:71], s[34:35] offset:-2048 sc1
	global_store_dwordx4 v2, v[56:59], s[34:35] offset:-1024 sc1
	global_store_dwordx4 v2, v[52:55], s[34:35] sc1
	global_store_dwordx4 v2, v[40:43], s[34:35] offset:1024 sc1
	global_store_dwordx4 v2, v[36:39], s[34:35] offset:2048 sc1
	global_store_dwordx4 v2, v[32:35], s[34:35] offset:3072 sc1
	s_nop 1
	s_waitcnt vmcnt(0)
	v_mov_b32_e32 v0, 0
	v_cmp_eq_u32_e32 vcc, 0, v6
	s_and_saveexec_b64 s[34:35], vcc
	s_cbranch_execz .LBB0_1339
	s_mov_b64 s[38:39], exec
	v_mbcnt_lo_u32_b32 v0, s38, 0
	v_mbcnt_hi_u32_b32 v0, s39, v0
	v_cmp_eq_u32_e32 vcc, 0, v0
	s_and_saveexec_b64 s[36:37], vcc
	s_cbranch_execz .LBB0_1338
	s_lshl_b32 s84, s81, 3
	s_ashr_i32 s85, s84, 31
	s_lshl_b64 s[84:85], s[84:85], 2
	s_add_u32 s84, s55, s84
	s_addc_u32 s85, s56, s85
	s_bcnt1_i32_b64 s15, s[38:39]
	v_mov_b32_e32 v1, s15
	global_atomic_add v1, v165, v1, s[84:85] sc0

; __device__ __forceinline__ bool splitk_fixup(f32x4 (&acc)[2][2][4][2], const Unit& u, const SplitK& sk, int wid, int lane_) {
;     ...
;     unsigned old = 0; if (lane == 0) old = __hip_atomic_fetch_add(sk.cnt + u.pn * 8 + wid, 1u, __ATOMIC_RELAXED, __HIP_MEMORY_SCOPE_AGENT);
;     old = (unsigned)__builtin_amdgcn_readfirstlane((int)old);
;     if ((old % (unsigned)u.nsplit) != (unsigned)(u.nsplit - 1)) return false;
; #pragma unroll
;     for (int q = 0; q < 32; ++q) acc[q >> 4][(q >> 3) & 1][(q >> 1) & 3][q & 1] = (f32x4){0.f, 0.f, 0.f, 0.f};
;     for (int sl = 0; sl < u.nsplit; ++sl) { u64* p = (u64*)(sk.part + ((size_t)(u.pn * u.nsplit + sl) * 8 + wid) * 8192) + lane;
.LBB0_1339:
	s_or_b64 exec, exec, s[34:35]
	v_cvt_f32_u32_e32 v1, s83
	s_sub_i32 s21, 0, s83
	v_readfirstlane_b32 s15, v0
	v_rcp_iflag_f32_e32 v1, v1
	s_nop 0
	v_mul_f32_e32 v1, 0x4f7ffffe, v1
	v_cvt_u32_f32_e32 v1, v1
	s_nop 0
	v_readfirstlane_b32 s34, v1
	s_mul_i32 s21, s21, s34
	s_mul_hi_u32 s21, s34, s21
	s_add_i32 s34, s34, s21
	s_mul_hi_u32 s21, s15, s34
	s_mul_i32 s21, s21, s83
	s_sub_i32 s15, s15, s21
	s_sub_i32 s21, s15, s83
	s_cmp_ge_u32 s15, s83
	s_cselect_b32 s15, s21, s15
	s_sub_i32 s21, s15, s83
	s_cmp_ge_u32 s15, s83
	s_cselect_b32 s15, s21, s15
	s_add_i32 s21, s83, -1
	s_cmp_lg_u32 s15, s21
	s_cbranch_scc1 .LBB0_1343
	v_mov_b32_e32 v32, 0
	v_mov_b32_e32 v33, 0
	v_mov_b32_e32 v34, 0
	v_mov_b32_e32 v35, 0
	v_mov_b32_e32 v36, 0
	v_mov_b32_e32 v37, 0
	v_mov_b32_e32 v38, 0
	v_mov_b32_e32 v39, 0
	v_mov_b32_e32 v40, 0
	v_mov_b32_e32 v41, 0
	v_mov_b32_e32 v42, 0
	v_mov_b32_e32 v43, 0
	v_mov_b32_e32 v52, 0
	v_mov_b32_e32 v53, 0
	v_mov_b32_e32 v54, 0
	v_mov_b32_e32 v55, 0
	v_mov_b32_e32 v56, 0
	v_mov_b32_e32 v57, 0
	v_mov_b32_e32 v58, 0
	v_mov_b32_e32 v59, 0
	v_mov_b32_e32 v68, 0
	v_mov_b32_e32 v69, 0
	v_mov_b32_e32 v70, 0
	v_mov_b32_e32 v71, 0
	v_mov_b32_e32 v72, 0
	v_mov_b32_e32 v73, 0
	v_mov_b32_e32 v74, 0
	v_mov_b32_e32 v75, 0
	v_mov_b32_e32 v84, 0
	v_mov_b32_e32 v85, 0
	v_mov_b32_e32 v86, 0
	v_mov_b32_e32 v87, 0
	v_mov_b32_e32 v44, 0
	v_mov_b32_e32 v45, 0
	v_mov_b32_e32 v46, 0
	v_mov_b32_e32 v47, 0
	v_mov_b32_e32 v48, 0
	v_mov_b32_e32 v49, 0
	v_mov_b32_e32 v50, 0
	v_mov_b32_e32 v51, 0
	v_mov_b32_e32 v60, 0
	v_mov_b32_e32 v61, 0
	v_mov_b32_e32 v62, 0
	v_mov_b32_e32 v63, 0
	v_mov_b32_e32 v64, 0
	v_mov_b32_e32 v65, 0
	v_mov_b32_e32 v66, 0
	v_mov_b32_e32 v67, 0
	v_mov_b32_e32 v76, 0
	v_mov_b32_e32 v77, 0
	v_mov_b32_e32 v78, 0
	v_mov_b32_e32 v79, 0
	v_mov_b32_e32 v80, 0
	v_mov_b32_e32 v81, 0
	v_mov_b32_e32 v82, 0
	v_mov_b32_e32 v83, 0
	v_mov_b32_e32 v88, 0
	v_mov_b32_e32 v89, 0
	v_mov_b32_e32 v90, 0
	v_mov_b32_e32 v91, 0
	v_mov_b32_e32 v92, 0
	v_mov_b32_e32 v93, 0
	v_mov_b32_e32 v94, 0
	v_mov_b32_e32 v95, 0
	v_mov_b32_e32 v96, 0
	v_mov_b32_e32 v97, 0
	v_mov_b32_e32 v98, 0
	v_mov_b32_e32 v99, 0
	v_mov_b32_e32 v100, 0
	v_mov_b32_e32 v101, 0
	v_mov_b32_e32 v102, 0
	v_mov_b32_e32 v103, 0
	v_mov_b32_e32 v104, 0
	v_mov_b32_e32 v105, 0
	v_mov_b32_e32 v106, 0
	v_mov_b32_e32 v107, 0
	v_mov_b32_e32 v116, 0
	v_mov_b32_e32 v117, 0
	v_mov_b32_e32 v118, 0
	v_mov_b32_e32 v119, 0
	v_mov_b32_e32 v120, 0
	v_mov_b32_e32 v121, 0
	v_mov_b32_e32 v122, 0
	v_mov_b32_e32 v123, 0
	v_mov_b32_e32 v132, 0
	v_mov_b32_e32 v133, 0
	v_mov_b32_e32 v134, 0
	v_mov_b32_e32 v135, 0
	v_mov_b32_e32 v136, 0
	v_mov_b32_e32 v137, 0
	v_mov_b32_e32 v138, 0
	v_mov_b32_e32 v139, 0
	v_mov_b32_e32 v148, 0
	v_mov_b32_e32 v149, 0
	v_mov_b32_e32 v150, 0
	v_mov_b32_e32 v151, 0
	v_mov_b32_e32 v108, 0
	v_mov_b32_e32 v109, 0
	v_mov_b32_e32 v110, 0
	v_mov_b32_e32 v111, 0
	v_mov_b32_e32 v112, 0
	v_mov_b32_e32 v113, 0
	v_mov_b32_e32 v114, 0
	v_mov_b32_e32 v115, 0
	v_mov_b32_e32 v124, 0
	v_mov_b32_e32 v125, 0
	v_mov_b32_e32 v126, 0
	v_mov_b32_e32 v127, 0
	v_mov_b32_e32 v128, 0
	v_mov_b32_e32 v129, 0
	v_mov_b32_e32 v130, 0
	v_mov_b32_e32 v131, 0
	v_mov_b32_e32 v140, 0
	v_mov_b32_e32 v141, 0
	v_mov_b32_e32 v142, 0
	v_mov_b32_e32 v143, 0
	v_mov_b32_e32 v144, 0
	v_mov_b32_e32 v145, 0
	v_mov_b32_e32 v146, 0
	v_mov_b32_e32 v147, 0
	v_mov_b32_e32 v152, 0
	v_mov_b32_e32 v153, 0
	v_mov_b32_e32 v154, 0
	v_mov_b32_e32 v155, 0
	v_mov_b32_e32 v156, 0
	v_mov_b32_e32 v157, 0
	v_mov_b32_e32 v158, 0
	v_mov_b32_e32 v159, 0
.LBB0_1341:
	v_and_b32_e32 v208, 63, v210
	v_lshlrev_b32_e32 v208, 4, v208
	v_add_u32_e32 v208, 0x1000, v208
	v_add_u32_e32 v209, 0x2000, v208
	v_add_u32_e32 v212, 0x4000, v208
	v_add_u32_e32 v213, 0x6000, v208
	s_ashr_i32 s21, s20, 31
	s_lshl_b64 s[22:23], s[20:21], 18
	s_add_u32 s22, s10, s22
	s_addc_u32 s23, s11, s23
	global_load_dwordx4 v[0:3], v208, s[22:23] offset:-4096 sc1
	global_load_dwordx4 v[4:7], v208, s[22:23] offset:-3072 sc1
	global_load_dwordx4 v[8:11], v208, s[22:23] offset:-2048 sc1
	global_load_dwordx4 v[12:15], v208, s[22:23] offset:-1024 sc1
	global_load_dwordx4 v[16:19], v208, s[22:23] sc1
	global_load_dwordx4 v[20:23], v208, s[22:23] offset:1024 sc1
	global_load_dwordx4 v[24:27], v208, s[22:23] offset:2048 sc1
	global_load_dwordx4 v[28:31], v208, s[22:23] offset:3072 sc1
	global_load_dwordx4 v[172:175], v209, s[22:23] offset:-4096 sc1
	global_load_dwordx4 v[176:179], v209, s[22:23] offset:-3072 sc1
	global_load_dwordx4 v[184:187], v209, s[22:23] offset:-2048 sc1
	global_load_dwordx4 v[188:191], v209, s[22:23] offset:-1024 sc1
	global_load_dwordx4 v[192:195], v209, s[22:23] sc1
	global_load_dwordx4 v[196:199], v209, s[22:23] offset:1024 sc1
	global_load_dwordx4 v[200:203], v209, s[22:23] offset:2048 sc1
	global_load_dwordx4 v[204:207], v209, s[22:23] offset:3072 sc1
; __device__ __forceinline__ bool splitk_fixup(f32x4 (&acc)[2][2][4][2], const Unit& u, const SplitK& sk, int wid, int lane_) {
;     ...
;     for (int sl = 0; sl < u.nsplit; ++sl) { u64* p = (u64*)(sk.part + ((size_t)(u.pn * u.nsplit + sl) * 8 + wid) * 8192) + lane;
; #pragma unroll
;         for (int q = 0; q < 32; ++q) { const u64 a = __hip_atomic_load(p + (2 * q) * 64, __ATOMIC_RELAXED, __HIP_MEMORY_SCOPE_AGENT), b = __hip_atomic_load(p + (2 * q + 1) * 64, __ATOMIC_RELAXED, __HIP_MEMORY_SCOPE_AGENT);
;             f32x4& d = acc[q >> 4][(q >> 3) & 1][(q >> 1) & 3][q & 1];
;             d[0] += __uint_as_float((unsigned)a); d[1] += __uint_as_float((unsigned)(a >> 32)); d[2] += __uint_as_float((unsigned)b); d[3] += __uint_as_float((unsigned)(b >> 32)); } }
.Lskr_p10_loop:
	s_add_i32 s83, s83, -1
	s_waitcnt vmcnt(15)
	v_add_f32_e32 v156, v156, v0
	v_add_f32_e32 v157, v157, v1
	v_add_f32_e32 v158, v158, v2
	v_add_f32_e32 v159, v159, v3
	global_load_dwordx4 v[0:3], v212, s[22:23] offset:-4096 sc1
	s_waitcnt vmcnt(15)
	v_add_f32_e32 v152, v152, v4
	v_add_f32_e32 v153, v153, v5
	v_add_f32_e32 v154, v154, v6
	v_add_f32_e32 v155, v155, v7
	global_load_dwordx4 v[4:7], v212, s[22:23] offset:-3072 sc1
	s_waitcnt vmcnt(15)
	v_add_f32_e32 v144, v144, v8
	v_add_f32_e32 v145, v145, v9
	v_add_f32_e32 v146, v146, v10
	v_add_f32_e32 v147, v147, v11
	global_load_dwordx4 v[8:11], v212, s[22:23] offset:-2048 sc1
	s_waitcnt vmcnt(15)
	v_add_f32_e32 v140, v140, v12
	v_add_f32_e32 v141, v141, v13
	v_add_f32_e32 v142, v142, v14
	v_add_f32_e32 v143, v143, v15
	global_load_dwordx4 v[12:15], v212, s[22:23] offset:-1024 sc1
	s_waitcnt vmcnt(15)
	v_add_f32_e32 v128, v128, v16
	v_add_f32_e32 v129, v129, v17
	v_add_f32_e32 v130, v130, v18
	v_add_f32_e32 v131, v131, v19
	global_load_dwordx4 v[16:19], v212, s[22:23] sc1
	s_waitcnt vmcnt(15)
	v_add_f32_e32 v124, v124, v20
	v_add_f32_e32 v125, v125, v21
	v_add_f32_e32 v126, v126, v22
	v_add_f32_e32 v127, v127, v23
	global_load_dwordx4 v[20:23], v212, s[22:23] offset:1024 sc1
	s_waitcnt vmcnt(15)
	v_add_f32_e32 v112, v112, v24
	v_add_f32_e32 v113, v113, v25
	v_add_f32_e32 v114, v114, v26
	v_add_f32_e32 v115, v115, v27
	global_load_dwordx4 v[24:27], v212, s[22:23] offset:2048 sc1
	s_waitcnt vmcnt(15)
	v_add_f32_e32 v108, v108, v28
	v_add_f32_e32 v109, v109, v29
	v_add_f32_e32 v110, v110, v30
	v_add_f32_e32 v111, v111, v31
	global_load_dwordx4 v[28:31], v212, s[22:23] offset:3072 sc1
	s_waitcnt vmcnt(15)
	v_add_f32_e32 v148, v148, v172
	v_add_f32_e32 v149, v149, v173
	v_add_f32_e32 v150, v150, v174
	v_add_f32_e32 v151, v151, v175
	global_load_dwordx4 v[172:175], v213, s[22:23] offset:-4096 sc1
	s_waitcnt vmcnt(15)
	v_add_f32_e32 v136, v136, v176
	v_add_f32_e32 v137, v137, v177
	v_add_f32_e32 v138, v138, v178
	v_add_f32_e32 v139, v139, v179
	global_load_dwordx4 v[176:179], v213, s[22:23] offset:-3072 sc1
	s_waitcnt vmcnt(15)
	v_add_f32_e32 v132, v132, v184
	v_add_f32_e32 v133, v133, v185
	v_add_f32_e32 v134, v134, v186
	v_add_f32_e32 v135, v135, v187
	global_load_dwordx4 v[184:187], v213, s[22:23] offset:-2048 sc1
	s_waitcnt vmcnt(15)
	v_add_f32_e32 v120, v120, v188
	v_add_f32_e32 v121, v121, v189
	v_add_f32_e32 v122, v122, v190
	v_add_f32_e32 v123, v123, v191
	global_load_dwordx4 v[188:191], v213, s[22:23] offset:-1024 sc1
	s_waitcnt vmcnt(15)
	v_add_f32_e32 v116, v116, v192
	v_add_f32_e32 v117, v117, v193
	v_add_f32_e32 v118, v118, v194
	v_add_f32_e32 v119, v119, v195
	global_load_dwordx4 v[192:195], v213, s[22:23] sc1
	s_waitcnt vmcnt(15)
	v_add_f32_e32 v104, v104, v196
	v_add_f32_e32 v105, v105, v197
	v_add_f32_e32 v106, v106, v198
	v_add_f32_e32 v107, v107, v199
	global_load_dwordx4 v[196:199], v213, s[22:23] offset:1024 sc1
	s_waitcnt vmcnt(15)
	v_add_f32_e32 v100, v100, v200
	v_add_f32_e32 v101, v101, v201
	v_add_f32_e32 v102, v102, v202
	v_add_f32_e32 v103, v103, v203
	global_load_dwordx4 v[200:203], v213, s[22:23] offset:2048 sc1
	s_waitcnt vmcnt(15)
	v_add_f32_e32 v96, v96, v204
	v_add_f32_e32 v97, v97, v205
	v_add_f32_e32 v98, v98, v206
	v_add_f32_e32 v99, v99, v207
	global_load_dwordx4 v[204:207], v213, s[22:23] offset:3072 sc1
	s_cmp_lg_u32 s83, 0
	s_addc_u32 s20, s20, 0
	s_ashr_i32 s21, s20, 31
	s_lshl_b64 s[22:23], s[20:21], 18
	s_add_u32 s22, s10, s22
	s_addc_u32 s23, s11, s23
	s_waitcnt vmcnt(15)
	v_add_f32_e32 v92, v92, v0
	v_add_f32_e32 v93, v93, v1
	v_add_f32_e32 v94, v94, v2
	v_add_f32_e32 v95, v95, v3
	global_load_dwordx4 v[0:3], v208, s[22:23] offset:-4096 sc1
	s_waitcnt vmcnt(15)
	v_add_f32_e32 v88, v88, v4
	v_add_f32_e32 v89, v89, v5
	v_add_f32_e32 v90, v90, v6
	v_add_f32_e32 v91, v91, v7
	global_load_dwordx4 v[4:7], v208, s[22:23] offset:-3072 sc1
	s_waitcnt vmcnt(15)
	v_add_f32_e32 v80, v80, v8
	v_add_f32_e32 v81, v81, v9
	v_add_f32_e32 v82, v82, v10
	v_add_f32_e32 v83, v83, v11
	global_load_dwordx4 v[8:11], v208, s[22:23] offset:-2048 sc1
	s_waitcnt vmcnt(15)
	v_add_f32_e32 v76, v76, v12
	v_add_f32_e32 v77, v77, v13
	v_add_f32_e32 v78, v78, v14
	v_add_f32_e32 v79, v79, v15
	global_load_dwordx4 v[12:15], v208, s[22:23] offset:-1024 sc1
	s_waitcnt vmcnt(15)
	v_add_f32_e32 v64, v64, v16
	v_add_f32_e32 v65, v65, v17
	v_add_f32_e32 v66, v66, v18
	v_add_f32_e32 v67, v67, v19
	global_load_dwordx4 v[16:19], v208, s[22:23] sc1
	s_waitcnt vmcnt(15)
	v_add_f32_e32 v60, v60, v20
	v_add_f32_e32 v61, v61, v21
	v_add_f32_e32 v62, v62, v22
	v_add_f32_e32 v63, v63, v23
	global_load_dwordx4 v[20:23], v208, s[22:23] offset:1024 sc1
	s_waitcnt vmcnt(15)
	v_add_f32_e32 v48, v48, v24
	v_add_f32_e32 v49, v49, v25
	v_add_f32_e32 v50, v50, v26
	v_add_f32_e32 v51, v51, v27
	global_load_dwordx4 v[24:27], v208, s[22:23] offset:2048 sc1
	s_waitcnt vmcnt(15)
	v_add_f32_e32 v44, v44, v28
	v_add_f32_e32 v45, v45, v29
	v_add_f32_e32 v46, v46, v30
	v_add_f32_e32 v47, v47, v31
	global_load_dwordx4 v[28:31], v208, s[22:23] offset:3072 sc1
	s_waitcnt vmcnt(15)
	v_add_f32_e32 v84, v84, v172
	v_add_f32_e32 v85, v85, v173
	v_add_f32_e32 v86, v86, v174
	v_add_f32_e32 v87, v87, v175
	global_load_dwordx4 v[172:175], v209, s[22:23] offset:-4096 sc1
	s_waitcnt vmcnt(15)
	v_add_f32_e32 v72, v72, v176
	v_add_f32_e32 v73, v73, v177
	v_add_f32_e32 v74, v74, v178
	v_add_f32_e32 v75, v75, v179
	global_load_dwordx4 v[176:179], v209, s[22:23] offset:-3072 sc1
	s_waitcnt vmcnt(15)
	v_add_f32_e32 v68, v68, v184
	v_add_f32_e32 v69, v69, v185
	v_add_f32_e32 v70, v70, v186
	v_add_f32_e32 v71, v71, v187
	global_load_dwordx4 v[184:187], v209, s[22:23] offset:-2048 sc1
	s_waitcnt vmcnt(15)
	v_add_f32_e32 v56, v56, v188
	v_add_f32_e32 v57, v57, v189
	v_add_f32_e32 v58, v58, v190
	v_add_f32_e32 v59, v59, v191
	global_load_dwordx4 v[188:191], v209, s[22:23] offset:-1024 sc1
	s_waitcnt vmcnt(15)
	v_add_f32_e32 v52, v52, v192
	v_add_f32_e32 v53, v53, v193
	v_add_f32_e32 v54, v54, v194
	v_add_f32_e32 v55, v55, v195
	global_load_dwordx4 v[192:195], v209, s[22:23] sc1
	s_waitcnt vmcnt(15)
	v_add_f32_e32 v40, v40, v196
	v_add_f32_e32 v41, v41, v197
	v_add_f32_e32 v42, v42, v198
	v_add_f32_e32 v43, v43, v199
	global_load_dwordx4 v[196:199], v209, s[22:23] offset:1024 sc1
	s_waitcnt vmcnt(15)
	v_add_f32_e32 v36, v36, v200
	v_add_f32_e32 v37, v37, v201
	v_add_f32_e32 v38, v38, v202
	v_add_f32_e32 v39, v39, v203
	global_load_dwordx4 v[200:203], v209, s[22:23] offset:2048 sc1
	s_waitcnt vmcnt(15)
	v_add_f32_e32 v32, v32, v204
	v_add_f32_e32 v33, v33, v205
	v_add_f32_e32 v34, v34, v206
	v_add_f32_e32 v35, v35, v207
	global_load_dwordx4 v[204:207], v209, s[22:23] offset:3072 sc1
	s_cmp_lg_u32 s83, 0
	s_cbranch_scc1 .Lskr_p10_loop
	s_waitcnt vmcnt(0)
	s_add_i32 s20, s20, 1
	s_mov_b64 s[22:23], -1
